# att work queue: next-row atomic issued behind first K loads, consumed at unit end
# speedup vs baseline: 1.0107x; 1.0032x over previous
.LBB0_1251:
	s_or_b64 exec, exec, s[8:9]
	s_waitcnt vmcnt(1)
	v_readfirstlane_b32 s8, v200
	s_cmp_gt_i32 s8, 0x101ff
	s_cbranch_scc1 .LBB0_1298
.LBB0_1252:
	v_mov_b32_e32 v120, v194
	s_cmp_gt_i32 s8, 0xffff
	v_readfirstlane_b32 s9, v120
	s_mov_b64 s[16:17], -1
	s_cbranch_scc0 .LBB0_1258
	s_add_i32 s16, s8, 0xffff0000
	s_lshr_b32 s16, s16, 4
	s_mul_hi_u32 s17, s16, 0x82000
	s_mul_i32 s16, s16, 0x82000
	s_add_u32 s20, s22, s16
	s_addc_u32 s21, s23, s17
	s_add_u32 s18, s24, s16
	s_addc_u32 s19, s25, s17
	s_mov_b64 s[16:17], 0

.LBB0_1264:
	s_or_b64 exec, exec, s[8:9]
	v_lshrrev_b32_e32 v122, 3, v117
	v_lshl_add_u32 v119, v122, 2, s47
	s_waitcnt lgkmcnt(0)
	ds_read2_b32 v[4:5], v119 offset1:8
	ds_read2_b32 v[12:13], v119 offset0:16 offset1:24
	v_lshlrev_b32_e32 v6, 4, v120
	s_add_u32 s8, s20, s42
	v_and_b32_e32 v118, 0x70, v6
	s_waitcnt lgkmcnt(1)
	v_lshlrev_b32_e32 v4, 9, v4
	v_lshlrev_b32_e32 v5, 9, v5
	s_waitcnt lgkmcnt(0)
	v_lshlrev_b32_e32 v12, 9, v12
	v_lshlrev_b32_e32 v13, 9, v13
	s_addc_u32 s9, s21, 0
	v_and_or_b32 v4, v4, s43, v118
	v_and_or_b32 v8, v5, s43, v118
	v_and_or_b32 v12, v12, s43, v118
	v_and_or_b32 v16, v13, s43, v118
	global_load_dwordx4 v[4:7], v4, s[8:9]
	s_nop 0
	global_load_dwordx4 v[8:11], v8, s[8:9]
	ds_read2_b32 v[20:21], v119 offset0:32 offset1:40
	global_load_dwordx4 v[12:15], v12, s[8:9]
	s_nop 0
	global_load_dwordx4 v[16:19], v16, s[8:9]
	ds_read2_b32 v[28:29], v119 offset0:48 offset1:56
	s_add_u32 s18, s18, s42
	s_addc_u32 s19, s19, 0
	s_waitcnt lgkmcnt(1)
	v_lshlrev_b32_e32 v20, 9, v20
	v_lshlrev_b32_e32 v21, 9, v21
	s_waitcnt lgkmcnt(0)
	v_lshlrev_b32_e32 v28, 9, v28
	v_lshlrev_b32_e32 v29, 9, v29
	v_and_or_b32 v20, v20, s43, v118
	v_and_or_b32 v24, v21, s43, v118
	v_and_or_b32 v28, v28, s43, v118
	v_and_or_b32 v32, v29, s43, v118
	global_load_dwordx4 v[20:23], v20, s[8:9]
	s_nop 0
	global_load_dwordx4 v[24:27], v24, s[8:9]
	ds_read2_b32 v[36:37], v119 offset0:64 offset1:72
	global_load_dwordx4 v[28:31], v28, s[8:9]
	s_nop 0
	global_load_dwordx4 v[32:35], v32, s[8:9]
	ds_read2_b32 v[44:45], v119 offset0:80 offset1:88
	s_waitcnt lgkmcnt(1)
	v_lshlrev_b32_e32 v36, 9, v36
	v_lshlrev_b32_e32 v37, 9, v37
	s_waitcnt lgkmcnt(0)
	v_lshlrev_b32_e32 v44, 9, v44
	v_lshlrev_b32_e32 v45, 9, v45
	v_and_or_b32 v36, v36, s43, v118
	v_and_or_b32 v40, v37, s43, v118
	v_and_or_b32 v44, v44, s43, v118
	v_and_or_b32 v48, v45, s43, v118
	global_load_dwordx4 v[36:39], v36, s[8:9]
	s_nop 0
	global_load_dwordx4 v[40:43], v40, s[8:9]
	s_nop 0
	global_load_dwordx4 v[44:47], v44, s[8:9]
	s_nop 0
	global_load_dwordx4 v[48:51], v48, s[8:9]
	ds_read2_b32 v[52:53], v119 offset0:96 offset1:104
	ds_read2_b32 v[64:65], v119 offset0:112 offset1:120
	v_add_u32_e32 v112, s47, v112
	v_add_u32_e32 v121, s47, v118
	v_mad_u32_u24 v123, v116, s44, v112
	s_waitcnt lgkmcnt(1)
	v_lshlrev_b32_e32 v52, 9, v52
	v_lshlrev_b32_e32 v53, 9, v53
	s_waitcnt lgkmcnt(0)
	v_lshlrev_b32_e32 v64, 9, v64
	v_lshlrev_b32_e32 v65, 9, v65
	v_and_or_b32 v52, v52, s43, v118
	v_and_or_b32 v60, v53, s43, v118
	v_and_or_b32 v64, v64, s43, v118
	v_and_or_b32 v68, v65, s43, v118
	global_load_dwordx4 v[52:55], v52, s[8:9]
	s_nop 0
	global_load_dwordx4 v[60:63], v60, s[8:9]
	s_nop 0
	global_load_dwordx4 v[64:67], v64, s[8:9]
	s_nop 0
	global_load_dwordx4 v[68:71], v68, s[8:9]
	s_and_saveexec_b64 s[98:99], s[6:7]
	v_mov_b32_e32 v200, 1
	global_atomic_add v200, v113, v200, s[12:13] sc0
	s_or_b64 exec, exec, s[98:99]
	v_mad_u32_u24 v132, v122, s44, v121
	s_waitcnt vmcnt(15)
	ds_write_b128 v132, v[4:7] offset:1024
	s_waitcnt vmcnt(14)
	ds_write_b128 v132, v[8:11] offset:2304
	s_waitcnt vmcnt(13)
	ds_write_b128 v132, v[12:15] offset:3584
	s_waitcnt vmcnt(12)
	ds_write_b128 v132, v[16:19] offset:4864
	ds_read_b128 v[4:7], v123 offset:1024
	ds_read_b128 v[8:11], v123 offset:1088
	ds_read_b128 v[12:15], v123 offset:3584
	ds_read_b128 v[16:19], v123 offset:3648
	ds_read2_b32 v[72:73], v119 offset0:128 offset1:136
	ds_read2_b32 v[74:75], v119 offset0:144 offset1:152
	s_waitcnt lgkmcnt(5)
	v_mfma_f32_16x16x32_bf16 v[4:7], v[4:7], v[0:3], 0
	s_waitcnt lgkmcnt(1)
	v_lshlrev_b32_e32 v72, 9, v72
	v_mfma_f32_16x16x32_bf16 v[108:111], v[8:11], v[56:59], v[4:7]
	v_mfma_f32_16x16x32_bf16 v[12:15], v[12:15], v[0:3], 0
	s_nop 3
	v_and_or_b32 v4, v72, s43, v118
	v_lshlrev_b32_e32 v5, 9, v73
	s_waitcnt lgkmcnt(0)
	v_lshlrev_b32_e32 v72, 9, v74
	v_lshlrev_b32_e32 v73, 9, v75
	v_and_or_b32 v8, v5, s43, v118
	v_and_or_b32 v72, v72, s43, v118
	v_and_or_b32 v76, v73, s43, v118
	global_load_dwordx4 v[4:7], v4, s[8:9]
	s_nop 0
	global_load_dwordx4 v[8:11], v8, s[8:9]
	s_nop 0
	global_load_dwordx4 v[72:75], v72, s[8:9]
	s_nop 0
	global_load_dwordx4 v[76:79], v76, s[8:9]
	v_mfma_f32_16x16x32_bf16 v[104:107], v[16:19], v[56:59], v[12:15]
	s_waitcnt vmcnt(15)
	ds_write_b128 v132, v[20:23] offset:1024
	s_waitcnt vmcnt(14)
	ds_write_b128 v132, v[24:27] offset:2304
	s_waitcnt vmcnt(13)
	ds_write_b128 v132, v[28:31] offset:3584
	s_waitcnt vmcnt(12)
	ds_write_b128 v132, v[32:35] offset:4864
	ds_read_b128 v[12:15], v123 offset:1024
	ds_read_b128 v[16:19], v123 offset:1088
	ds_read_b128 v[20:23], v123 offset:3584
	ds_read_b128 v[24:27], v123 offset:3648
	ds_read2_b32 v[28:29], v119 offset0:160 offset1:168
	ds_read2_b32 v[30:31], v119 offset0:176 offset1:184
	s_waitcnt lgkmcnt(5)
	v_mfma_f32_16x16x32_bf16 v[12:15], v[12:15], v[0:3], 0
	s_waitcnt lgkmcnt(1)
	v_lshlrev_b32_e32 v28, 9, v28
	v_mfma_f32_16x16x32_bf16 v[100:103], v[16:19], v[56:59], v[12:15]
	v_mfma_f32_16x16x32_bf16 v[20:23], v[20:23], v[0:3], 0
	s_nop 3
	v_and_or_b32 v12, v28, s43, v118
	v_lshlrev_b32_e32 v13, 9, v29
	s_waitcnt lgkmcnt(0)
	v_lshlrev_b32_e32 v28, 9, v30
	v_lshlrev_b32_e32 v29, 9, v31
	v_and_or_b32 v16, v13, s43, v118
	v_and_or_b32 v28, v28, s43, v118
	v_and_or_b32 v32, v29, s43, v118
	global_load_dwordx4 v[12:15], v12, s[8:9]
	s_nop 0
	global_load_dwordx4 v[16:19], v16, s[8:9]
	s_nop 0
	global_load_dwordx4 v[28:31], v28, s[8:9]
	s_nop 0
	global_load_dwordx4 v[32:35], v32, s[8:9]
	v_mfma_f32_16x16x32_bf16 v[96:99], v[24:27], v[56:59], v[20:23]
	s_waitcnt vmcnt(15)
	ds_write_b128 v132, v[36:39] offset:1024
	s_waitcnt vmcnt(14)
	ds_write_b128 v132, v[40:43] offset:2304
	s_waitcnt vmcnt(13)
	ds_write_b128 v132, v[44:47] offset:3584
	s_waitcnt vmcnt(12)
	ds_write_b128 v132, v[48:51] offset:4864
	ds_read_b128 v[20:23], v123 offset:1024
	ds_read_b128 v[24:27], v123 offset:1088
	ds_read_b128 v[36:39], v123 offset:3584
	ds_read_b128 v[40:43], v123 offset:3648
	ds_read2_b32 v[44:45], v119 offset0:192 offset1:200
	ds_read2_b32 v[46:47], v119 offset0:208 offset1:216
	s_waitcnt lgkmcnt(5)
	v_mfma_f32_16x16x32_bf16 v[20:23], v[20:23], v[0:3], 0
	s_waitcnt lgkmcnt(1)
	v_lshlrev_b32_e32 v44, 9, v44
	v_mfma_f32_16x16x32_bf16 v[92:95], v[24:27], v[56:59], v[20:23]
	v_mfma_f32_16x16x32_bf16 v[36:39], v[36:39], v[0:3], 0
	s_nop 3
	v_and_or_b32 v20, v44, s43, v118
	v_lshlrev_b32_e32 v21, 9, v45
	s_waitcnt lgkmcnt(0)
	v_lshlrev_b32_e32 v44, 9, v46
	v_lshlrev_b32_e32 v45, 9, v47
	v_and_or_b32 v24, v21, s43, v118
	v_and_or_b32 v44, v44, s43, v118
	v_and_or_b32 v48, v45, s43, v118
	global_load_dwordx4 v[20:23], v20, s[8:9]
	s_nop 0
	global_load_dwordx4 v[24:27], v24, s[8:9]
	s_nop 0
	global_load_dwordx4 v[44:47], v44, s[8:9]
	s_nop 0
	global_load_dwordx4 v[48:51], v48, s[8:9]
	v_mfma_f32_16x16x32_bf16 v[88:91], v[40:43], v[56:59], v[36:39]
	s_waitcnt vmcnt(15)
	ds_write_b128 v132, v[52:55] offset:1024
	s_waitcnt vmcnt(14)
	ds_write_b128 v132, v[60:63] offset:2304
	s_waitcnt vmcnt(13)
	ds_write_b128 v132, v[64:67] offset:3584
	s_waitcnt vmcnt(12)
	ds_write_b128 v132, v[68:71] offset:4864
	ds_read_b128 v[36:39], v123 offset:1024
	ds_read_b128 v[40:43], v123 offset:1088
	ds_read_b128 v[52:55], v123 offset:3584
	ds_read_b128 v[60:63], v123 offset:3648
	ds_read2_b32 v[64:65], v119 offset0:224 offset1:232
	ds_read2_b32 v[66:67], v119 offset0:240 offset1:248
	s_waitcnt lgkmcnt(5)
	v_mfma_f32_16x16x32_bf16 v[36:39], v[36:39], v[0:3], 0
	s_waitcnt lgkmcnt(1)
	v_lshlrev_b32_e32 v64, 9, v64
	v_mfma_f32_16x16x32_bf16 v[84:87], v[40:43], v[56:59], v[36:39]
	v_mfma_f32_16x16x32_bf16 v[52:55], v[52:55], v[0:3], 0
	s_nop 3
	v_and_or_b32 v36, v64, s43, v118
	v_lshlrev_b32_e32 v37, 9, v65
	s_waitcnt lgkmcnt(0)
	v_lshlrev_b32_e32 v64, 9, v66
	v_and_or_b32 v40, v37, s43, v118
	v_and_or_b32 v64, v64, s43, v118
	v_lshlrev_b32_e32 v65, 9, v67
	global_load_dwordx4 v[36:39], v36, s[8:9]
	s_nop 0
	global_load_dwordx4 v[40:43], v40, s[8:9]
	v_and_or_b32 v65, v65, s43, v118
	global_load_dwordx4 v[124:127], v64, s[8:9]
	global_load_dwordx4 v[128:131], v65, s[8:9]
	v_mfma_f32_16x16x32_bf16 v[80:83], v[60:63], v[56:59], v[52:55]
	s_waitcnt vmcnt(15)
	ds_write_b128 v132, v[4:7] offset:1024
	s_waitcnt vmcnt(14)
	ds_write_b128 v132, v[8:11] offset:2304
	s_waitcnt vmcnt(13)
	ds_write_b128 v132, v[72:75] offset:3584
	s_waitcnt vmcnt(12)
	ds_write_b128 v132, v[76:79] offset:4864
	ds_read_b128 v[4:7], v123 offset:1024
	ds_read_b128 v[8:11], v123 offset:1088
	ds_read_b128 v[52:55], v123 offset:3584
	ds_read_b128 v[60:63], v123 offset:3648
	s_waitcnt lgkmcnt(3)
	v_mfma_f32_16x16x32_bf16 v[4:7], v[4:7], v[0:3], 0
	s_waitcnt lgkmcnt(1)
	v_mfma_f32_16x16x32_bf16 v[52:55], v[52:55], v[0:3], 0
	v_mfma_f32_16x16x32_bf16 v[76:79], v[8:11], v[56:59], v[4:7]
	s_waitcnt lgkmcnt(0)
	v_mfma_f32_16x16x32_bf16 v[72:75], v[60:63], v[56:59], v[52:55]
	s_waitcnt vmcnt(11)
	ds_write_b128 v132, v[12:15] offset:1024
	s_waitcnt vmcnt(10)
	ds_write_b128 v132, v[16:19] offset:2304
	s_waitcnt vmcnt(9)
	ds_write_b128 v132, v[28:31] offset:3584
	s_waitcnt vmcnt(8)
	ds_write_b128 v132, v[32:35] offset:4864
	ds_read_b128 v[4:7], v123 offset:1024
	ds_read_b128 v[8:11], v123 offset:1088
	ds_read_b128 v[12:15], v123 offset:3584
	ds_read_b128 v[16:19], v123 offset:3648
	s_waitcnt lgkmcnt(3)
	v_mfma_f32_16x16x32_bf16 v[4:7], v[4:7], v[0:3], 0
	s_waitcnt lgkmcnt(1)
	v_mfma_f32_16x16x32_bf16 v[12:15], v[12:15], v[0:3], 0
	v_mfma_f32_16x16x32_bf16 v[68:71], v[8:11], v[56:59], v[4:7]
	s_waitcnt lgkmcnt(0)
	v_mfma_f32_16x16x32_bf16 v[64:67], v[16:19], v[56:59], v[12:15]
	s_waitcnt vmcnt(7)
	ds_write_b128 v132, v[20:23] offset:1024
	s_waitcnt vmcnt(6)
	ds_write_b128 v132, v[24:27] offset:2304
	s_waitcnt vmcnt(5)
	ds_write_b128 v132, v[44:47] offset:3584
	s_waitcnt vmcnt(4)
	ds_write_b128 v132, v[48:51] offset:4864
	ds_read_b128 v[4:7], v123 offset:1024
	ds_read_b128 v[8:11], v123 offset:1088
	ds_read_b128 v[12:15], v123 offset:3584
	ds_read_b128 v[16:19], v123 offset:3648
	s_waitcnt lgkmcnt(3)
	v_mfma_f32_16x16x32_bf16 v[4:7], v[4:7], v[0:3], 0
	s_waitcnt lgkmcnt(1)
	v_mfma_f32_16x16x32_bf16 v[12:15], v[12:15], v[0:3], 0
	v_mfma_f32_16x16x32_bf16 v[60:63], v[8:11], v[56:59], v[4:7]
	s_waitcnt lgkmcnt(0)
	v_mfma_f32_16x16x32_bf16 v[52:55], v[16:19], v[56:59], v[12:15]
	s_waitcnt vmcnt(3)
	ds_write_b128 v132, v[36:39] offset:1024
	s_waitcnt vmcnt(2)
	ds_write_b128 v132, v[40:43] offset:2304
	s_waitcnt vmcnt(1)
	ds_write_b128 v132, v[124:127] offset:3584
	s_waitcnt vmcnt(0)
	ds_write_b128 v132, v[128:131] offset:4864
	ds_read_b128 v[4:7], v123 offset:1024
	ds_read_b128 v[8:11], v123 offset:1088
	ds_read_b128 v[12:15], v123 offset:3584
	ds_read_b128 v[124:127], v123 offset:3648
	s_waitcnt lgkmcnt(3)
	v_mfma_f32_16x16x32_bf16 v[4:7], v[4:7], v[0:3], 0
	s_waitcnt lgkmcnt(1)
	v_mfma_f32_16x16x32_bf16 v[128:131], v[12:15], v[0:3], 0
	ds_read2_b32 v[0:1], v119 offset1:8
	ds_read2_b32 v[2:3], v119 offset0:16 offset1:24
	s_waitcnt lgkmcnt(1)
	v_lshlrev_b32_e32 v0, 9, v0
	v_and_or_b32 v0, v0, s43, v118
	v_lshlrev_b32_e32 v1, 9, v1
	v_and_or_b32 v1, v1, s43, v118
	global_load_dwordx4 v[32:35], v0, s[18:19]
	global_load_dwordx4 v[36:39], v1, s[18:19]
	s_waitcnt lgkmcnt(0)
	v_lshlrev_b32_e32 v0, 9, v2
	v_and_or_b32 v2, v0, s43, v118
	ds_read2_b32 v[0:1], v119 offset0:32 offset1:40
	v_lshlrev_b32_e32 v3, 9, v3
	v_and_or_b32 v3, v3, s43, v118
	global_load_dwordx4 v[40:43], v2, s[18:19]
	global_load_dwordx4 v[44:47], v3, s[18:19]
	ds_read2_b32 v[2:3], v119 offset0:48 offset1:56
	s_waitcnt lgkmcnt(1)
	v_lshlrev_b32_e32 v0, 9, v0
	v_and_or_b32 v0, v0, s43, v118
	v_lshlrev_b32_e32 v1, 9, v1
	v_and_or_b32 v1, v1, s43, v118
	global_load_dwordx4 v[16:19], v0, s[18:19]
	global_load_dwordx4 v[20:23], v1, s[18:19]
	s_waitcnt lgkmcnt(0)
	v_lshlrev_b32_e32 v0, 9, v2
	v_and_or_b32 v2, v0, s43, v118
	v_lshlrev_b32_e32 v3, 9, v3
	v_mfma_f32_16x16x32_bf16 v[48:51], v[8:11], v[56:59], v[4:7]
	ds_read2_b32 v[0:1], v119 offset0:64 offset1:72
	v_and_or_b32 v3, v3, s43, v118
	global_load_dwordx4 v[24:27], v2, s[18:19]
	global_load_dwordx4 v[28:31], v3, s[18:19]
	ds_read2_b32 v[8:9], v119 offset0:80 offset1:88
	v_mfma_f32_16x16x32_bf16 v[56:59], v[124:127], v[56:59], v[128:131]
	s_waitcnt lgkmcnt(1)
	v_lshlrev_b32_e32 v0, 9, v0
	v_lshlrev_b32_e32 v1, 9, v1
	v_and_or_b32 v0, v0, s43, v118
	s_waitcnt lgkmcnt(0)
	v_lshlrev_b32_e32 v8, 9, v8
	v_lshlrev_b32_e32 v9, 9, v9
	v_and_or_b32 v4, v1, s43, v118
	v_and_or_b32 v8, v8, s43, v118
	v_and_or_b32 v12, v9, s43, v118
	global_load_dwordx4 v[0:3], v0, s[18:19]
	s_nop 0
	global_load_dwordx4 v[4:7], v4, s[18:19]
	s_nop 0
	global_load_dwordx4 v[8:11], v8, s[18:19]
	s_nop 0
	global_load_dwordx4 v[12:15], v12, s[18:19]
	v_and_b32_e32 v123, 12, v116
	v_add_u32_e32 v123, v112, v123
	v_and_b32_e32 v112, 3, v120
	v_lshl_add_u32 v112, v112, 2, s41
	ds_read_b32 v136, v123
	ds_read_b32 v137, v123 offset:64
	ds_read_b32 v138, v123 offset:128
	ds_read_b32 v139, v123 offset:192
	ds_read_b32 v140, v123 offset:256
	ds_read_b32 v141, v123 offset:320
	ds_read_b32 v142, v123 offset:384
	ds_read_b32 v143, v123 offset:448
	ds_read_b32 v144, v123 offset:512
	ds_read_b32 v145, v123 offset:576
	ds_read_b32 v146, v123 offset:640
	ds_read_b32 v147, v123 offset:704
	ds_read_b32 v148, v123 offset:768
	ds_read_b32 v149, v123 offset:832
	ds_read_b32 v150, v123 offset:896
	ds_read_b32 v151, v123 offset:960
	s_movk_i32 s8, 0x7c0
	v_mov_b32_e32 v168, 0xf149f2ca
	v_mov_b32_dpp v108, v109 row_shr:4 row_mask:0xf bank_mask:0x2
	v_mov_b32_dpp v104, v105 row_shr:4 row_mask:0xf bank_mask:0x2
	v_mov_b32_dpp v100, v101 row_shr:4 row_mask:0xf bank_mask:0x2
	v_mov_b32_dpp v96, v97 row_shr:4 row_mask:0xf bank_mask:0x2
	v_mov_b32_dpp v92, v93 row_shr:4 row_mask:0xf bank_mask:0x2
	v_mov_b32_dpp v88, v89 row_shr:4 row_mask:0xf bank_mask:0x2
	v_mov_b32_dpp v84, v85 row_shr:4 row_mask:0xf bank_mask:0x2
	v_mov_b32_dpp v80, v81 row_shr:4 row_mask:0xf bank_mask:0x2
	v_mov_b32_dpp v76, v77 row_shr:4 row_mask:0xf bank_mask:0x2
	v_mov_b32_dpp v72, v73 row_shr:4 row_mask:0xf bank_mask:0x2
	v_mov_b32_dpp v68, v69 row_shr:4 row_mask:0xf bank_mask:0x2
	v_mov_b32_dpp v64, v65 row_shr:4 row_mask:0xf bank_mask:0x2
	v_mov_b32_dpp v60, v61 row_shr:4 row_mask:0xf bank_mask:0x2
	v_mov_b32_dpp v52, v53 row_shr:4 row_mask:0xf bank_mask:0x2
	v_mov_b32_dpp v48, v49 row_shr:4 row_mask:0xf bank_mask:0x2
	v_mov_b32_dpp v56, v57 row_shr:4 row_mask:0xf bank_mask:0x2
	v_mov_b32_dpp v108, v110 row_shr:8 row_mask:0xf bank_mask:0x4
	v_mov_b32_dpp v104, v106 row_shr:8 row_mask:0xf bank_mask:0x4
	v_mov_b32_dpp v100, v102 row_shr:8 row_mask:0xf bank_mask:0x4
	v_mov_b32_dpp v96, v98 row_shr:8 row_mask:0xf bank_mask:0x4
	v_mov_b32_dpp v92, v94 row_shr:8 row_mask:0xf bank_mask:0x4
	v_mov_b32_dpp v88, v90 row_shr:8 row_mask:0xf bank_mask:0x4
	v_mov_b32_dpp v84, v86 row_shr:8 row_mask:0xf bank_mask:0x4
	v_mov_b32_dpp v80, v82 row_shr:8 row_mask:0xf bank_mask:0x4
	v_mov_b32_dpp v76, v78 row_shr:8 row_mask:0xf bank_mask:0x4
	v_mov_b32_dpp v72, v74 row_shr:8 row_mask:0xf bank_mask:0x4
	v_mov_b32_dpp v68, v70 row_shr:8 row_mask:0xf bank_mask:0x4
	v_mov_b32_dpp v64, v66 row_shr:8 row_mask:0xf bank_mask:0x4
	v_mov_b32_dpp v60, v62 row_shr:8 row_mask:0xf bank_mask:0x4
	v_mov_b32_dpp v52, v54 row_shr:8 row_mask:0xf bank_mask:0x4
	v_mov_b32_dpp v48, v50 row_shr:8 row_mask:0xf bank_mask:0x4
	v_mov_b32_dpp v56, v58 row_shr:8 row_mask:0xf bank_mask:0x4
	v_mov_b32_dpp v108, v111 row_shr:12 row_mask:0xf bank_mask:0x8
	v_mov_b32_dpp v104, v107 row_shr:12 row_mask:0xf bank_mask:0x8
	v_mov_b32_dpp v100, v103 row_shr:12 row_mask:0xf bank_mask:0x8
	v_mov_b32_dpp v96, v99 row_shr:12 row_mask:0xf bank_mask:0x8
	v_mov_b32_dpp v92, v95 row_shr:12 row_mask:0xf bank_mask:0x8
	v_mov_b32_dpp v88, v91 row_shr:12 row_mask:0xf bank_mask:0x8
	v_mov_b32_dpp v84, v87 row_shr:12 row_mask:0xf bank_mask:0x8
	v_mov_b32_dpp v80, v83 row_shr:12 row_mask:0xf bank_mask:0x8
	v_mov_b32_dpp v76, v79 row_shr:12 row_mask:0xf bank_mask:0x8
	v_mov_b32_dpp v72, v75 row_shr:12 row_mask:0xf bank_mask:0x8
	v_mov_b32_dpp v68, v71 row_shr:12 row_mask:0xf bank_mask:0x8
	v_mov_b32_dpp v64, v67 row_shr:12 row_mask:0xf bank_mask:0x8
	v_mov_b32_dpp v60, v63 row_shr:12 row_mask:0xf bank_mask:0x8
	v_mov_b32_dpp v52, v55 row_shr:12 row_mask:0xf bank_mask:0x8
	v_mov_b32_dpp v48, v51 row_shr:12 row_mask:0xf bank_mask:0x8
	v_mov_b32_dpp v56, v59 row_shr:12 row_mask:0xf bank_mask:0x8
	s_waitcnt lgkmcnt(15)
	v_lshrrev_b32_e32 v152, 10, v136
	v_and_or_b32 v152, v152, s8, v112
	s_waitcnt lgkmcnt(14)
	v_lshrrev_b32_e32 v153, 10, v137
	v_and_or_b32 v153, v153, s8, v112
	s_waitcnt lgkmcnt(13)
	v_lshrrev_b32_e32 v154, 10, v138
	v_and_or_b32 v154, v154, s8, v112
	s_waitcnt lgkmcnt(12)
	v_lshrrev_b32_e32 v155, 10, v139
	v_and_or_b32 v155, v155, s8, v112
	s_waitcnt lgkmcnt(11)
	v_lshrrev_b32_e32 v156, 10, v140
	v_and_or_b32 v156, v156, s8, v112
	s_waitcnt lgkmcnt(10)
	v_lshrrev_b32_e32 v157, 10, v141
	v_and_or_b32 v157, v157, s8, v112
	s_waitcnt lgkmcnt(9)
	v_lshrrev_b32_e32 v158, 10, v142
	v_and_or_b32 v158, v158, s8, v112
	s_waitcnt lgkmcnt(8)
	v_lshrrev_b32_e32 v159, 10, v143
	v_and_or_b32 v159, v159, s8, v112
	s_waitcnt lgkmcnt(7)
	v_lshrrev_b32_e32 v160, 10, v144
	v_and_or_b32 v160, v160, s8, v112
	s_waitcnt lgkmcnt(6)
	v_lshrrev_b32_e32 v161, 10, v145
	v_and_or_b32 v161, v161, s8, v112
	s_waitcnt lgkmcnt(5)
	v_lshrrev_b32_e32 v162, 10, v146
	v_and_or_b32 v162, v162, s8, v112
	s_waitcnt lgkmcnt(4)
	v_lshrrev_b32_e32 v163, 10, v147
	v_and_or_b32 v163, v163, s8, v112
	s_waitcnt lgkmcnt(3)
	v_lshrrev_b32_e32 v164, 10, v148
	v_and_or_b32 v164, v164, s8, v112
	s_waitcnt lgkmcnt(2)
	v_lshrrev_b32_e32 v165, 10, v149
	v_and_or_b32 v165, v165, s8, v112
	s_waitcnt lgkmcnt(1)
	v_lshrrev_b32_e32 v166, 10, v150
	v_and_or_b32 v166, v166, s8, v112
	s_waitcnt lgkmcnt(0)
	v_lshrrev_b32_e32 v167, 10, v151
	v_and_or_b32 v167, v167, s8, v112
	ds_read_b32 v152, v152
	ds_read_b32 v153, v153
	ds_read_b32 v154, v154
	ds_read_b32 v155, v155
	ds_read_b32 v156, v156
	ds_read_b32 v157, v157
	ds_read_b32 v158, v158
	ds_read_b32 v159, v159
	ds_read_b32 v160, v160
	ds_read_b32 v161, v161
	ds_read_b32 v162, v162
	ds_read_b32 v163, v163
	ds_read_b32 v164, v164
	ds_read_b32 v165, v165
	ds_read_b32 v166, v166
	ds_read_b32 v167, v167
	s_waitcnt lgkmcnt(15)
	v_fmac_f32_e32 v152, 0x3e000000, v108
	v_cmp_lt_u32_e64 s[20:21], s45, v136
	s_waitcnt lgkmcnt(14)
	v_fmac_f32_e32 v153, 0x3e000000, v104
	v_cmp_lt_u32_e64 s[8:9], s45, v137
	v_cndmask_b32_e64 v110, v168, v152, s[20:21]
	s_waitcnt lgkmcnt(13)
	v_fmac_f32_e32 v154, 0x3e000000, v100
	v_cmp_lt_u32_e64 s[20:21], s45, v138
	v_cndmask_b32_e64 v109, v168, v153, s[8:9]
	s_waitcnt lgkmcnt(12)
	v_fmac_f32_e32 v155, 0x3e000000, v96
	v_cmp_lt_u32_e64 s[8:9], s45, v139
	v_cndmask_b32_e64 v102, v168, v154, s[20:21]
	s_waitcnt lgkmcnt(11)
	v_fmac_f32_e32 v156, 0x3e000000, v92
	v_cmp_lt_u32_e64 s[20:21], s45, v140
	v_cndmask_b32_e64 v101, v168, v155, s[8:9]
	s_waitcnt lgkmcnt(10)
	v_fmac_f32_e32 v157, 0x3e000000, v88
	v_cmp_lt_u32_e64 s[8:9], s45, v141
	v_cndmask_b32_e64 v94, v168, v156, s[20:21]
	s_waitcnt lgkmcnt(9)
	v_fmac_f32_e32 v158, 0x3e000000, v84
	v_cmp_lt_u32_e64 s[20:21], s45, v142
	v_cndmask_b32_e64 v93, v168, v157, s[8:9]
	s_waitcnt lgkmcnt(8)
	v_fmac_f32_e32 v159, 0x3e000000, v80
	v_cmp_lt_u32_e64 s[8:9], s45, v143
	v_cndmask_b32_e64 v86, v168, v158, s[20:21]
	s_waitcnt lgkmcnt(7)
	v_fmac_f32_e32 v160, 0x3e000000, v76
	v_cmp_lt_u32_e64 s[20:21], s45, v144
	v_cndmask_b32_e64 v85, v168, v159, s[8:9]
	s_waitcnt lgkmcnt(6)
	v_fmac_f32_e32 v161, 0x3e000000, v72
	v_cmp_lt_u32_e64 s[8:9], s45, v145
	v_cndmask_b32_e64 v78, v168, v160, s[20:21]
	s_waitcnt lgkmcnt(5)
	v_fmac_f32_e32 v162, 0x3e000000, v68
	v_cmp_lt_u32_e64 s[20:21], s45, v146
	v_cndmask_b32_e64 v77, v168, v161, s[8:9]
	s_waitcnt lgkmcnt(4)
	v_fmac_f32_e32 v163, 0x3e000000, v64
	v_cmp_lt_u32_e64 s[8:9], s45, v147
	v_cndmask_b32_e64 v70, v168, v162, s[20:21]
	s_waitcnt lgkmcnt(3)
	v_fmac_f32_e32 v164, 0x3e000000, v60
	v_cmp_lt_u32_e64 s[20:21], s45, v148
	v_cndmask_b32_e64 v69, v168, v163, s[8:9]
	s_waitcnt lgkmcnt(2)
	v_fmac_f32_e32 v165, 0x3e000000, v52
	v_cmp_lt_u32_e64 s[8:9], s45, v149
	v_cndmask_b32_e64 v62, v168, v164, s[20:21]
	s_waitcnt lgkmcnt(1)
	v_fmac_f32_e32 v166, 0x3e000000, v48
	v_cmp_lt_u32_e64 s[20:21], s45, v150
	v_cndmask_b32_e64 v61, v168, v165, s[8:9]
	s_waitcnt lgkmcnt(0)
	v_fmac_f32_e32 v167, 0x3e000000, v56
	v_cmp_lt_u32_e64 s[8:9], s45, v151
	v_cndmask_b32_e64 v50, v168, v166, s[20:21]
	s_nop 1
	v_cndmask_b32_e64 v49, v168, v167, s[8:9]
	v_max3_f32 v48, v110, s46, v109
	v_max3_f32 v48, v48, v102, v101
	v_max3_f32 v48, v48, v94, v93
	v_max3_f32 v48, v48, v86, v85
	v_max3_f32 v48, v48, v78, v77
	v_max3_f32 v48, v48, v70, v69
	v_max3_f32 v48, v48, v62, v61
	v_max3_f32 v48, v48, v50, v49
	v_mov_b32_e32 v51, v113
	v_mov_b32_e32 v68, v113
	v_bfe_u32 v98, v120, 4, 2
	v_mov_b32_dpp v51, v48 row_ror:4 row_mask:0xf bank_mask:0xf
	v_max_f32_e32 v51, v51, v51
	v_max_f32_e32 v48, v48, v51
	v_mov_b32_e32 v51, v113
	v_lshrrev_b32_e32 v100, 2, v116
	v_lshl_or_b32 v98, v98, 2, v100
	v_mov_b32_dpp v51, v48 row_ror:8 row_mask:0xf bank_mask:0xf
	v_max_f32_e32 v51, v51, v51
	v_max_f32_e32 v48, v48, v51
	v_mov_b32_e32 v51, v48
	s_nop 1
	v_permlane16_swap_b32_e32 v48, v51
	v_max_f32_e32 v51, v51, v51
	v_max_f32_e32 v48, v48, v48
	v_max_f32_e32 v48, v48, v51
	v_mov_b32_e32 v51, v48
	s_nop 1
	v_permlane32_swap_b32_e32 v48, v51
	v_max_f32_e32 v51, v51, v51
	v_max_f32_e32 v48, v48, v48
	v_max_f32_e32 v48, v48, v51
	v_sub_f32_e32 v51, v110, v48
	v_mul_f32_e32 v51, 0x3fb8aa3b, v51
	v_sub_f32_e32 v52, v109, v48
	v_exp_f32_e32 v51, v51
	v_mul_f32_e32 v52, 0x3fb8aa3b, v52
	v_sub_f32_e32 v53, v102, v48
	v_exp_f32_e32 v52, v52
	v_mul_f32_e32 v53, 0x3fb8aa3b, v53
	v_sub_f32_e32 v54, v101, v48
	v_exp_f32_e32 v53, v53
	v_mul_f32_e32 v54, 0x3fb8aa3b, v54
	v_sub_f32_e32 v56, v94, v48
	v_exp_f32_e32 v54, v54
	v_mul_f32_e32 v56, 0x3fb8aa3b, v56
	v_sub_f32_e32 v57, v93, v48
	v_add_f32_e32 v55, 0, v51
	v_exp_f32_e32 v56, v56
	v_mul_f32_e32 v57, 0x3fb8aa3b, v57
	v_sub_f32_e32 v58, v86, v48
	v_add_f32_e32 v55, v52, v55
	v_exp_f32_e32 v57, v57
	v_mul_f32_e32 v58, 0x3fb8aa3b, v58
	v_sub_f32_e32 v59, v85, v48
	v_add_f32_e32 v55, v53, v55
	v_exp_f32_e32 v58, v58
	v_mul_f32_e32 v59, 0x3fb8aa3b, v59
	v_sub_f32_e32 v60, v78, v48
	v_add_f32_e32 v55, v54, v55
	v_exp_f32_e32 v59, v59
	v_mul_f32_e32 v60, 0x3fb8aa3b, v60
	v_sub_f32_e32 v63, v77, v48
	v_sub_f32_e32 v64, v70, v48
	v_add_f32_e32 v55, v56, v55
	v_exp_f32_e32 v60, v60
	v_mul_f32_e32 v63, 0x3fb8aa3b, v63
	v_mul_f32_e32 v64, 0x3fb8aa3b, v64
	v_add_f32_e32 v55, v57, v55
	v_exp_f32_e32 v63, v63
	v_exp_f32_e32 v101, v64
	v_sub_f32_e32 v64, v69, v48
	v_add_f32_e32 v55, v58, v55
	v_mul_f32_e32 v64, 0x3fb8aa3b, v64
	v_sub_f32_e32 v62, v62, v48
	v_add_f32_e32 v55, v59, v55
	v_exp_f32_e32 v102, v64
	v_mul_f32_e32 v62, 0x3fb8aa3b, v62
	v_sub_f32_e32 v61, v61, v48
	v_add_f32_e32 v55, v60, v55
	v_exp_f32_e32 v103, v62
	v_mul_f32_e32 v61, 0x3fb8aa3b, v61
	v_sub_f32_e32 v50, v50, v48
	v_add_f32_e32 v55, v63, v55
	v_exp_f32_e32 v104, v61
	v_mul_f32_e32 v50, 0x3fb8aa3b, v50
	v_sub_f32_e32 v48, v49, v48
	v_add_f32_e32 v55, v101, v55
	v_exp_f32_e32 v105, v50
	v_mul_f32_e32 v48, 0x3fb8aa3b, v48
	v_add_f32_e32 v55, v102, v55
	v_exp_f32_e32 v106, v48
	v_add_f32_e32 v48, v103, v55
	v_add_f32_e32 v48, v104, v48
	v_add_f32_e32 v48, v105, v48
	v_add_f32_e32 v48, v106, v48
	v_mov_b32_e32 v50, v113
	v_mov_b32_e32 v55, v113
	v_add_f32_dpp v48, v48, v48 row_ror:4 row_mask:0xf bank_mask:0xf bound_ctrl:1
	v_mov_b32_e32 v61, v113
	v_mov_b32_dpp v50, v51 row_shl:8 row_mask:0xf bank_mask:0x1 bound_ctrl:1
	v_add_f32_dpp v48, v48, v48 row_ror:8 row_mask:0xf bank_mask:0xf bound_ctrl:1
	v_mov_b32_e32 v49, v48
	s_nop 1
	v_permlane16_swap_b32_e32 v48, v49
	v_add_f32_e32 v96, v48, v49
	v_mov_b32_e32 v49, v113
	v_cndmask_b32_e32 v48, 0, v51, vcc
	v_mov_b32_dpp v55, v51 row_shl:12 row_mask:0xf bank_mask:0x1 bound_ctrl:1
	v_mov_b32_dpp v49, v51 row_shl:4 row_mask:0xf bank_mask:0x1 bound_ctrl:1
	v_cndmask_b32_e32 v51, 0, v52, vcc
	v_mov_b32_dpp v61, v52 row_shl:4 row_mask:0xf bank_mask:0x1 bound_ctrl:1
	v_mov_b32_e32 v62, v113
	v_mov_b32_e32 v64, v113
	v_cvt_pk_bf16_f32 v76, v48, v49
	v_cvt_pk_bf16_f32 v77, v50, v55
	v_cvt_pk_bf16_f32 v78, v51, v61
	v_mov_b32_e32 v49, v113
	v_mov_b32_e32 v50, v113
	v_mov_b32_e32 v51, v113
	v_mov_b32_dpp v62, v52 row_shl:8 row_mask:0xf bank_mask:0x1 bound_ctrl:1
	v_mov_b32_dpp v64, v52 row_shl:12 row_mask:0xf bank_mask:0x1 bound_ctrl:1
	v_cndmask_b32_e32 v48, 0, v53, vcc
	v_mov_b32_dpp v49, v53 row_shl:4 row_mask:0xf bank_mask:0x1 bound_ctrl:1
	v_mov_b32_dpp v50, v53 row_shl:8 row_mask:0xf bank_mask:0x1 bound_ctrl:1
	v_mov_b32_dpp v51, v53 row_shl:12 row_mask:0xf bank_mask:0x1 bound_ctrl:1
	v_cvt_pk_bf16_f32 v79, v62, v64
	v_mov_b32_e32 v53, v113
	v_cvt_pk_bf16_f32 v64, v48, v49
	v_cvt_pk_bf16_f32 v65, v50, v51
	v_mov_b32_e32 v49, v113
	v_mov_b32_e32 v50, v113
	v_mov_b32_e32 v51, v113
	v_cndmask_b32_e32 v52, 0, v54, vcc
	v_mov_b32_dpp v53, v54 row_shl:4 row_mask:0xf bank_mask:0x1 bound_ctrl:1
	v_cndmask_b32_e32 v48, 0, v56, vcc
	v_mov_b32_dpp v49, v56 row_shl:4 row_mask:0xf bank_mask:0x1 bound_ctrl:1
	v_mov_b32_dpp v50, v56 row_shl:8 row_mask:0xf bank_mask:0x1 bound_ctrl:1
	v_mov_b32_dpp v51, v56 row_shl:12 row_mask:0xf bank_mask:0x1 bound_ctrl:1
	v_cvt_pk_bf16_f32 v66, v52, v53
	v_cvt_pk_bf16_f32 v52, v48, v49
	v_cvt_pk_bf16_f32 v53, v50, v51
	v_mov_b32_e32 v51, v113
	ds_read2_b32 v[48:49], v119 offset0:96 offset1:104
	v_cndmask_b32_e32 v50, 0, v58, vcc
	v_mov_b32_dpp v51, v58 row_shl:4 row_mask:0xf bank_mask:0x1 bound_ctrl:1
	v_cvt_pk_bf16_f32 v72, v50, v51
	ds_read2_b32 v[50:51], v119 offset0:112 offset1:120
	s_waitcnt lgkmcnt(1)
	v_lshlrev_b32_e32 v48, 9, v48
	v_and_or_b32 v48, v48, s43, v118
	v_lshlrev_b32_e32 v49, 9, v49
	v_and_or_b32 v49, v49, s43, v118
	global_load_dwordx4 v[80:83], v48, s[18:19]
	global_load_dwordx4 v[84:87], v49, s[18:19]
	s_waitcnt lgkmcnt(0)
	v_lshlrev_b32_e32 v48, 9, v50
	v_and_or_b32 v48, v48, s43, v118
	v_lshlrev_b32_e32 v49, 9, v51
	v_and_or_b32 v49, v49, s43, v118
	global_load_dwordx4 v[88:91], v48, s[18:19]
	global_load_dwordx4 v[92:95], v49, s[18:19]
	v_mov_b32_e32 v55, v113
	v_mov_b32_e32 v61, v113
	v_mov_b32_e32 v56, v113
	v_mov_b32_dpp v55, v54 row_shl:8 row_mask:0xf bank_mask:0x1 bound_ctrl:1
	v_mov_b32_dpp v61, v54 row_shl:12 row_mask:0xf bank_mask:0x1 bound_ctrl:1
	v_cvt_pk_bf16_f32 v67, v55, v61
	v_mov_b32_e32 v55, v113
	v_mov_b32_e32 v61, v113
	v_cndmask_b32_e32 v54, 0, v57, vcc
	v_mov_b32_dpp v55, v57 row_shl:4 row_mask:0xf bank_mask:0x1 bound_ctrl:1
	v_mov_b32_dpp v56, v57 row_shl:8 row_mask:0xf bank_mask:0x1 bound_ctrl:1
	v_mov_b32_dpp v61, v57 row_shl:12 row_mask:0xf bank_mask:0x1 bound_ctrl:1
	v_cvt_pk_bf16_f32 v54, v54, v55
	v_cvt_pk_bf16_f32 v55, v56, v61
	v_mov_b32_e32 v56, v113
	v_mov_b32_e32 v57, v113
	v_mov_b32_e32 v61, v113
	v_mov_b32_dpp v56, v58 row_shl:8 row_mask:0xf bank_mask:0x1 bound_ctrl:1
	v_mov_b32_dpp v57, v58 row_shl:12 row_mask:0xf bank_mask:0x1 bound_ctrl:1
	v_cndmask_b32_e32 v58, 0, v59, vcc
	v_mov_b32_dpp v61, v59 row_shl:4 row_mask:0xf bank_mask:0x1 bound_ctrl:1
	v_mov_b32_e32 v62, v113
	v_mov_b32_dpp v68, v59 row_shl:12 row_mask:0xf bank_mask:0x1 bound_ctrl:1
	v_cvt_pk_bf16_f32 v74, v58, v61
	v_mov_b32_dpp v62, v59 row_shl:8 row_mask:0xf bank_mask:0x1 bound_ctrl:1
	v_mov_b32_e32 v49, v113
	v_mov_b32_e32 v50, v113
	v_mov_b32_e32 v51, v113
	v_mov_b32_e32 v58, v113
	v_mov_b32_e32 v59, v113
	v_cvt_pk_bf16_f32 v73, v56, v57
	v_cndmask_b32_e32 v48, 0, v60, vcc
	v_mov_b32_dpp v49, v60 row_shl:4 row_mask:0xf bank_mask:0x1 bound_ctrl:1
	v_mov_b32_dpp v50, v60 row_shl:8 row_mask:0xf bank_mask:0x1 bound_ctrl:1
	v_mov_b32_dpp v51, v60 row_shl:12 row_mask:0xf bank_mask:0x1 bound_ctrl:1
	v_mov_b32_e32 v57, v113
	v_mov_b32_dpp v58, v63 row_shl:8 row_mask:0xf bank_mask:0x1 bound_ctrl:1
	v_mov_b32_dpp v59, v63 row_shl:12 row_mask:0xf bank_mask:0x1 bound_ctrl:1
	v_cvt_pk_bf16_f32 v75, v62, v68
	v_cndmask_b32_e32 v56, 0, v63, vcc
	v_mov_b32_dpp v57, v63 row_shl:4 row_mask:0xf bank_mask:0x1 bound_ctrl:1
	v_cvt_pk_bf16_f32 v68, v48, v49
	v_cvt_pk_bf16_f32 v69, v50, v51
	v_cvt_pk_bf16_f32 v71, v58, v59
	v_mov_b32_e32 v49, v113
	v_mov_b32_e32 v50, v113
	v_mov_b32_e32 v51, v113
	v_mov_b32_e32 v58, v113
	v_mov_b32_e32 v59, v113
	v_cvt_pk_bf16_f32 v70, v56, v57
	v_cndmask_b32_e32 v48, 0, v101, vcc
	v_mov_b32_dpp v49, v101 row_shl:4 row_mask:0xf bank_mask:0x1 bound_ctrl:1
	v_mov_b32_dpp v50, v101 row_shl:8 row_mask:0xf bank_mask:0x1 bound_ctrl:1
	v_mov_b32_dpp v51, v101 row_shl:12 row_mask:0xf bank_mask:0x1 bound_ctrl:1
	v_mov_b32_e32 v57, v113
	v_mov_b32_dpp v58, v102 row_shl:8 row_mask:0xf bank_mask:0x1 bound_ctrl:1
	v_mov_b32_dpp v59, v102 row_shl:12 row_mask:0xf bank_mask:0x1 bound_ctrl:1
	v_cndmask_b32_e32 v56, 0, v102, vcc
	v_mov_b32_dpp v57, v102 row_shl:4 row_mask:0xf bank_mask:0x1 bound_ctrl:1
	v_cvt_pk_bf16_f32 v60, v48, v49
	v_cvt_pk_bf16_f32 v61, v50, v51
	v_cvt_pk_bf16_f32 v63, v58, v59
	v_mov_b32_e32 v49, v113
	v_mov_b32_e32 v50, v113
	v_mov_b32_e32 v51, v113
	v_mov_b32_e32 v59, v113
	v_mov_b32_e32 v101, v113
	v_mov_b32_e32 v102, v113
	v_cndmask_b32_e32 v48, 0, v103, vcc
	v_mov_b32_dpp v49, v103 row_shl:4 row_mask:0xf bank_mask:0x1 bound_ctrl:1
	v_mov_b32_dpp v50, v103 row_shl:8 row_mask:0xf bank_mask:0x1 bound_ctrl:1
	v_mov_b32_dpp v51, v103 row_shl:12 row_mask:0xf bank_mask:0x1 bound_ctrl:1
	v_cndmask_b32_e32 v58, 0, v104, vcc
	v_mov_b32_dpp v59, v104 row_shl:4 row_mask:0xf bank_mask:0x1 bound_ctrl:1
	v_mov_b32_dpp v101, v104 row_shl:8 row_mask:0xf bank_mask:0x1 bound_ctrl:1
	v_mov_b32_dpp v102, v104 row_shl:12 row_mask:0xf bank_mask:0x1 bound_ctrl:1
	v_cvt_pk_bf16_f32 v62, v56, v57
	v_cvt_pk_bf16_f32 v56, v48, v49
	v_cvt_pk_bf16_f32 v57, v50, v51
	v_cvt_pk_bf16_f32 v58, v58, v59
	v_cvt_pk_bf16_f32 v59, v101, v102
	v_mov_b32_e32 v49, v113
	v_mov_b32_e32 v50, v113
	v_mov_b32_e32 v51, v113
	v_mov_b32_e32 v102, v113
	v_mov_b32_e32 v103, v113
	v_mov_b32_e32 v104, v113
	v_lshlrev_b32_e32 v100, 3, v120
	v_mov_b32_e32 v97, v96
	v_cndmask_b32_e32 v48, 0, v105, vcc
	v_mov_b32_dpp v49, v105 row_shl:4 row_mask:0xf bank_mask:0x1 bound_ctrl:1
	v_mov_b32_dpp v50, v105 row_shl:8 row_mask:0xf bank_mask:0x1 bound_ctrl:1
	v_mov_b32_dpp v51, v105 row_shl:12 row_mask:0xf bank_mask:0x1 bound_ctrl:1
	v_cndmask_b32_e32 v101, 0, v106, vcc
	v_mov_b32_dpp v102, v106 row_shl:4 row_mask:0xf bank_mask:0x1 bound_ctrl:1
	v_mov_b32_dpp v103, v106 row_shl:8 row_mask:0xf bank_mask:0x1 bound_ctrl:1
	v_mov_b32_dpp v104, v106 row_shl:12 row_mask:0xf bank_mask:0x1 bound_ctrl:1
	v_mul_u32_u24_e32 v98, 0xa0, v98
	v_and_b32_e32 v100, 24, v100
	v_mul_u32_u24_e32 v99, 0xa0, v122
	v_permlane32_swap_b32_e32 v96, v97
	v_cvt_pk_bf16_f32 v48, v48, v49
	v_cvt_pk_bf16_f32 v49, v50, v51
	v_cvt_pk_bf16_f32 v50, v101, v102
	v_cvt_pk_bf16_f32 v51, v103, v104
	v_add3_u32 v110, s47, v98, v100
	v_add_u32_e32 v111, v121, v99
	s_waitcnt vmcnt(15)
	ds_write_b128 v111, v[32:35] offset:1024
	s_waitcnt vmcnt(14)
	ds_write_b128 v111, v[36:39] offset:2304
	s_waitcnt vmcnt(13)
	ds_write_b128 v111, v[40:43] offset:3584
	s_waitcnt vmcnt(12)
	ds_write_b128 v111, v[44:47] offset:4864
	ds_read_b64_tr_b16 v[34:35], v110 offset:3584
	ds_read_b64_tr_b16 v[32:33], v110 offset:1024
	ds_read_b64_tr_b16 v[36:37], v110 offset:1056
	ds_read_b64_tr_b16 v[40:41], v110 offset:1088
	ds_read_b64_tr_b16 v[44:45], v110 offset:1120
	ds_read_b64_tr_b16 v[38:39], v110 offset:3616
	ds_read_b64_tr_b16 v[42:43], v110 offset:3648
	ds_read_b64_tr_b16 v[46:47], v110 offset:3680
	ds_read2_b32 v[98:99], v119 offset0:128 offset1:136
	ds_read2_b32 v[106:107], v119 offset0:144 offset1:152
	s_waitcnt lgkmcnt(8)
	v_mfma_f32_16x16x32_bf16 v[32:35], v[76:79], v[32:35], 0
	s_waitcnt lgkmcnt(1)
	v_lshlrev_b32_e32 v98, 9, v98
	v_and_or_b32 v108, v98, s43, v118
	v_lshlrev_b32_e32 v98, 9, v99
	s_waitcnt lgkmcnt(0)
	v_lshlrev_b32_e32 v106, 9, v106
	v_and_or_b32 v109, v98, s43, v118
	v_and_or_b32 v112, v106, s43, v118
	v_lshlrev_b32_e32 v106, 9, v107
	global_load_dwordx4 v[98:101], v108, s[18:19]
	global_load_dwordx4 v[102:105], v109, s[18:19]
	v_and_or_b32 v124, v106, s43, v118
	global_load_dwordx4 v[106:109], v112, s[18:19]
	global_load_dwordx4 v[120:123], v124, s[18:19]
	v_mfma_f32_16x16x32_bf16 v[36:39], v[76:79], v[36:39], 0
	v_mfma_f32_16x16x32_bf16 v[40:43], v[76:79], v[40:43], 0
	v_mfma_f32_16x16x32_bf16 v[44:47], v[76:79], v[44:47], 0
	s_waitcnt vmcnt(15)
	ds_write_b128 v111, v[16:19] offset:1024
	s_waitcnt vmcnt(14)
	ds_write_b128 v111, v[20:23] offset:2304
	s_waitcnt vmcnt(13)
	ds_write_b128 v111, v[24:27] offset:3584
	s_waitcnt vmcnt(12)
	ds_write_b128 v111, v[28:31] offset:4864
	ds_read_b64_tr_b16 v[18:19], v110 offset:3584
	ds_read_b64_tr_b16 v[16:17], v110 offset:1024
	ds_read_b64_tr_b16 v[20:21], v110 offset:1056
	ds_read_b64_tr_b16 v[24:25], v110 offset:1088
	ds_read_b64_tr_b16 v[28:29], v110 offset:1120
	ds_read_b64_tr_b16 v[22:23], v110 offset:3616
	ds_read_b64_tr_b16 v[26:27], v110 offset:3648
	ds_read_b64_tr_b16 v[30:31], v110 offset:3680
	s_waitcnt lgkmcnt(6)
	v_mfma_f32_16x16x32_bf16 v[16:19], v[64:67], v[16:19], v[32:35]
	s_waitcnt lgkmcnt(1)
	v_mfma_f32_16x16x32_bf16 v[24:27], v[64:67], v[24:27], v[40:43]
	s_nop 0
	ds_read2_b32 v[32:33], v119 offset0:160 offset1:168
	s_waitcnt lgkmcnt(0)
	v_lshlrev_b32_e32 v32, 9, v32
	ds_read2_b32 v[40:41], v119 offset0:176 offset1:184
	v_lshlrev_b32_e32 v33, 9, v33
	v_mfma_f32_16x16x32_bf16 v[20:23], v[64:67], v[20:23], v[36:39]
	v_and_or_b32 v32, v32, s43, v118
	s_waitcnt lgkmcnt(0)
	v_lshlrev_b32_e32 v40, 9, v40
	v_and_or_b32 v36, v33, s43, v118
	v_and_or_b32 v112, v40, s43, v118
	v_lshlrev_b32_e32 v40, 9, v41
	global_load_dwordx4 v[32:35], v32, s[18:19]
	s_nop 0
	global_load_dwordx4 v[36:39], v36, s[18:19]
	v_and_or_b32 v124, v40, s43, v118
	global_load_dwordx4 v[40:43], v112, s[18:19]
	global_load_dwordx4 v[76:79], v124, s[18:19]
	v_mfma_f32_16x16x32_bf16 v[28:31], v[64:67], v[28:31], v[44:47]
	s_waitcnt vmcnt(15)
	ds_write_b128 v111, v[0:3] offset:1024
	s_waitcnt vmcnt(14)
	ds_write_b128 v111, v[4:7] offset:2304
	s_waitcnt vmcnt(13)
	ds_write_b128 v111, v[8:11] offset:3584
	s_waitcnt vmcnt(12)
	ds_write_b128 v111, v[12:15] offset:4864
	ds_read_b64_tr_b16 v[2:3], v110 offset:3584
	ds_read_b64_tr_b16 v[0:1], v110 offset:1024
	ds_read_b64_tr_b16 v[4:5], v110 offset:1056
	ds_read_b64_tr_b16 v[8:9], v110 offset:1088
	ds_read_b64_tr_b16 v[12:13], v110 offset:1120
	ds_read_b64_tr_b16 v[6:7], v110 offset:3616
	ds_read_b64_tr_b16 v[10:11], v110 offset:3648
	ds_read_b64_tr_b16 v[14:15], v110 offset:3680
	s_waitcnt lgkmcnt(6)
	v_mfma_f32_16x16x32_bf16 v[0:3], v[52:55], v[0:3], v[16:19]
	s_waitcnt lgkmcnt(1)
	v_mfma_f32_16x16x32_bf16 v[8:11], v[52:55], v[8:11], v[24:27]
	s_nop 0
	ds_read2_b32 v[16:17], v119 offset0:192 offset1:200
	s_waitcnt lgkmcnt(0)
	v_lshlrev_b32_e32 v16, 9, v16
	ds_read2_b32 v[24:25], v119 offset0:208 offset1:216
	v_lshlrev_b32_e32 v17, 9, v17
	v_mfma_f32_16x16x32_bf16 v[4:7], v[52:55], v[4:7], v[20:23]
	v_and_or_b32 v16, v16, s43, v118
	s_waitcnt lgkmcnt(0)
	v_lshlrev_b32_e32 v24, 9, v24
	v_and_or_b32 v20, v17, s43, v118
	v_and_or_b32 v64, v24, s43, v118
	v_lshlrev_b32_e32 v24, 9, v25
	global_load_dwordx4 v[16:19], v16, s[18:19]
	s_nop 0
	global_load_dwordx4 v[20:23], v20, s[18:19]
	v_and_or_b32 v65, v24, s43, v118
	global_load_dwordx4 v[24:27], v64, s[18:19]
	global_load_dwordx4 v[44:47], v65, s[18:19]
	v_mfma_f32_16x16x32_bf16 v[12:15], v[52:55], v[12:15], v[28:31]
	s_waitcnt vmcnt(15)
	ds_write_b128 v111, v[80:83] offset:1024
	s_waitcnt vmcnt(14)
	ds_write_b128 v111, v[84:87] offset:2304
	s_waitcnt vmcnt(13)
	ds_write_b128 v111, v[88:91] offset:3584
	s_waitcnt vmcnt(12)
	ds_write_b128 v111, v[92:95] offset:4864
	ds_read_b64_tr_b16 v[30:31], v110 offset:3584
	ds_read_b64_tr_b16 v[28:29], v110 offset:1024
	ds_read_b64_tr_b16 v[52:53], v110 offset:1056
	ds_read_b64_tr_b16 v[64:65], v110 offset:1088
	ds_read_b64_tr_b16 v[80:81], v110 offset:1120
	ds_read_b64_tr_b16 v[54:55], v110 offset:3616
	ds_read_b64_tr_b16 v[66:67], v110 offset:3648
	ds_read_b64_tr_b16 v[82:83], v110 offset:3680
	s_waitcnt lgkmcnt(6)
	v_mfma_f32_16x16x32_bf16 v[0:3], v[72:75], v[28:31], v[0:3]
	ds_read2_b32 v[28:29], v119 offset0:224 offset1:232
	s_waitcnt lgkmcnt(0)
	v_lshlrev_b32_e32 v28, 9, v28
	v_mfma_f32_16x16x32_bf16 v[8:11], v[72:75], v[64:67], v[8:11]
	ds_read2_b32 v[64:65], v119 offset0:240 offset1:248
	v_and_or_b32 v66, v28, s43, v118
	v_lshlrev_b32_e32 v28, 9, v29
	v_and_or_b32 v67, v28, s43, v118
	v_mfma_f32_16x16x32_bf16 v[4:7], v[72:75], v[52:55], v[4:7]
	s_waitcnt lgkmcnt(0)
	v_lshlrev_b32_e32 v64, 9, v64
	v_and_or_b32 v88, v64, s43, v118
	v_lshlrev_b32_e32 v64, 9, v65
	global_load_dwordx4 v[28:31], v66, s[18:19]
	global_load_dwordx4 v[52:55], v67, s[18:19]
	v_and_or_b32 v89, v64, s43, v118
	global_load_dwordx4 v[64:67], v88, s[18:19]
	global_load_dwordx4 v[84:87], v89, s[18:19]
	v_mfma_f32_16x16x32_bf16 v[12:15], v[72:75], v[80:83], v[12:15]
	s_waitcnt vmcnt(15)
	ds_write_b128 v111, v[98:101] offset:1024
	s_waitcnt vmcnt(14)
	ds_write_b128 v111, v[102:105] offset:2304
	s_waitcnt vmcnt(13)
	ds_write_b128 v111, v[106:109] offset:3584
	s_waitcnt vmcnt(12)
	ds_write_b128 v111, v[120:123] offset:4864
	ds_read_b64_tr_b16 v[74:75], v110 offset:3584
	ds_read_b64_tr_b16 v[72:73], v110 offset:1024
	ds_read_b64_tr_b16 v[80:81], v110 offset:1056
	ds_read_b64_tr_b16 v[88:89], v110 offset:1088
	ds_read_b64_tr_b16 v[92:93], v110 offset:1120
	ds_read_b64_tr_b16 v[82:83], v110 offset:3616
	ds_read_b64_tr_b16 v[90:91], v110 offset:3648
	ds_read_b64_tr_b16 v[94:95], v110 offset:3680
	s_waitcnt lgkmcnt(6)
	v_mfma_f32_16x16x32_bf16 v[0:3], v[68:71], v[72:75], v[0:3]
	s_waitcnt lgkmcnt(2)
	v_mfma_f32_16x16x32_bf16 v[4:7], v[68:71], v[80:83], v[4:7]
	s_waitcnt lgkmcnt(1)
	v_mfma_f32_16x16x32_bf16 v[8:11], v[68:71], v[88:91], v[8:11]
	s_waitcnt lgkmcnt(0)
	v_mfma_f32_16x16x32_bf16 v[12:15], v[68:71], v[92:95], v[12:15]
	s_waitcnt vmcnt(11)
	ds_write_b128 v111, v[32:35] offset:1024
	s_waitcnt vmcnt(10)
	ds_write_b128 v111, v[36:39] offset:2304
	s_waitcnt vmcnt(9)
	ds_write_b128 v111, v[40:43] offset:3584
	s_waitcnt vmcnt(8)
	ds_write_b128 v111, v[76:79] offset:4864
	ds_read_b64_tr_b16 v[34:35], v110 offset:3584
	ds_read_b64_tr_b16 v[32:33], v110 offset:1024
	ds_read_b64_tr_b16 v[36:37], v110 offset:1056
	ds_read_b64_tr_b16 v[40:41], v110 offset:1088
	ds_read_b64_tr_b16 v[68:69], v110 offset:1120
	ds_read_b64_tr_b16 v[38:39], v110 offset:3616
	ds_read_b64_tr_b16 v[42:43], v110 offset:3648
	ds_read_b64_tr_b16 v[70:71], v110 offset:3680
	s_waitcnt lgkmcnt(6)
	v_mfma_f32_16x16x32_bf16 v[0:3], v[60:63], v[32:35], v[0:3]
	s_waitcnt lgkmcnt(2)
	v_mfma_f32_16x16x32_bf16 v[4:7], v[60:63], v[36:39], v[4:7]
	s_waitcnt lgkmcnt(1)
	v_mfma_f32_16x16x32_bf16 v[8:11], v[60:63], v[40:43], v[8:11]
	s_waitcnt lgkmcnt(0)
	v_mfma_f32_16x16x32_bf16 v[12:15], v[60:63], v[68:71], v[12:15]
	s_waitcnt vmcnt(7)
	ds_write_b128 v111, v[16:19] offset:1024
	s_waitcnt vmcnt(6)
	ds_write_b128 v111, v[20:23] offset:2304
	s_waitcnt vmcnt(5)
	ds_write_b128 v111, v[24:27] offset:3584
	s_waitcnt vmcnt(4)
	ds_write_b128 v111, v[44:47] offset:4864
	ds_read_b64_tr_b16 v[18:19], v110 offset:3584
	ds_read_b64_tr_b16 v[16:17], v110 offset:1024
	ds_read_b64_tr_b16 v[20:21], v110 offset:1056
	ds_read_b64_tr_b16 v[24:25], v110 offset:1088
	ds_read_b64_tr_b16 v[32:33], v110 offset:1120
	ds_read_b64_tr_b16 v[22:23], v110 offset:3616
	ds_read_b64_tr_b16 v[26:27], v110 offset:3648
	ds_read_b64_tr_b16 v[34:35], v110 offset:3680
	s_waitcnt lgkmcnt(6)
	v_mfma_f32_16x16x32_bf16 v[0:3], v[56:59], v[16:19], v[0:3]
	s_waitcnt lgkmcnt(2)
	v_mfma_f32_16x16x32_bf16 v[4:7], v[56:59], v[20:23], v[4:7]
	s_waitcnt lgkmcnt(1)
	v_mfma_f32_16x16x32_bf16 v[8:11], v[56:59], v[24:27], v[8:11]
	s_waitcnt lgkmcnt(0)
	v_mfma_f32_16x16x32_bf16 v[16:19], v[56:59], v[32:35], v[12:15]
	s_waitcnt vmcnt(3)
	ds_write_b128 v111, v[28:31] offset:1024
	s_waitcnt vmcnt(2)
	ds_write_b128 v111, v[52:55] offset:2304
	s_waitcnt vmcnt(1)
	ds_write_b128 v111, v[64:67] offset:3584
	s_waitcnt vmcnt(0)
	ds_write_b128 v111, v[84:87] offset:4864
	ds_read_b64_tr_b16 v[14:15], v110 offset:3584
	ds_read_b64_tr_b16 v[12:13], v110 offset:1024
	ds_read_b64_tr_b16 v[20:21], v110 offset:1056
	ds_read_b64_tr_b16 v[24:25], v110 offset:1088
	ds_read_b64_tr_b16 v[28:29], v110 offset:1120
	ds_read_b64_tr_b16 v[22:23], v110 offset:3616
	ds_read_b64_tr_b16 v[26:27], v110 offset:3648
	ds_read_b64_tr_b16 v[30:31], v110 offset:3680
	s_waitcnt lgkmcnt(6)
	v_mfma_f32_16x16x32_bf16 v[12:15], v[48:51], v[12:15], v[0:3]
	v_cmp_gt_u32_e32 vcc, 16, v117
	s_waitcnt lgkmcnt(1)
	v_mfma_f32_16x16x32_bf16 v[0:3], v[48:51], v[24:27], v[8:11]
	s_waitcnt lgkmcnt(0)
	v_mfma_f32_16x16x32_bf16 v[8:11], v[48:51], v[28:31], v[16:19]
	s_nop 2
	v_add_f32_e32 v19, v96, v97
	ds_bpermute_b32 v16, v114, v19
	ds_bpermute_b32 v17, v114, v19 offset:4
	ds_bpermute_b32 v18, v114, v19 offset:8
	ds_bpermute_b32 v19, v114, v19 offset:12
	v_mfma_f32_16x16x32_bf16 v[4:7], v[48:51], v[20:23], v[4:7]
	s_and_saveexec_b64 s[8:9], vcc
	s_cbranch_execz .LBB0_1251
	s_waitcnt lgkmcnt(0)
	v_div_scale_f32 v20, s[18:19], v19, v19, 1.0
	v_rcp_f32_e32 v21, v20
	v_div_scale_f32 v22, vcc, 1.0, v19, 1.0
	v_lshlrev_b32_e32 v112, 1, v116
	v_fma_f32 v23, -v20, v21, 1.0
	v_fmac_f32_e32 v21, v23, v21
	v_mul_f32_e32 v23, v22, v21
	v_fma_f32 v24, -v20, v23, v22
	v_fmac_f32_e32 v23, v24, v21
	v_fma_f32 v20, -v20, v23, v22
	v_div_scale_f32 v22, s[18:19], v18, v18, 1.0
	v_rcp_f32_e32 v24, v22
	v_div_fmas_f32 v20, v20, v21, v23
	v_div_fixup_f32 v19, v20, v19, 1.0
	v_fma_f32 v20, -v22, v24, 1.0
	v_fmac_f32_e32 v24, v20, v24
	v_div_scale_f32 v20, vcc, 1.0, v18, 1.0
	v_mul_f32_e32 v21, v20, v24
	v_fma_f32 v23, -v22, v21, v20
	v_fmac_f32_e32 v21, v23, v24
	v_fma_f32 v20, -v22, v21, v20
	v_div_scale_f32 v22, s[18:19], v17, v17, 1.0
	v_rcp_f32_e32 v23, v22
	v_div_fmas_f32 v20, v20, v24, v21
	v_div_fixup_f32 v18, v20, v18, 1.0
	v_fma_f32 v20, -v22, v23, 1.0
	v_fmac_f32_e32 v23, v20, v23
	v_div_scale_f32 v20, vcc, 1.0, v17, 1.0
	v_mul_f32_e32 v21, v20, v23
	v_fma_f32 v24, -v22, v21, v20
	v_fmac_f32_e32 v21, v24, v23
	v_fma_f32 v20, -v22, v21, v20
	v_div_scale_f32 v22, s[18:19], v16, v16, 1.0
	v_rcp_f32_e32 v24, v22
	v_div_fmas_f32 v20, v20, v23, v21
	v_div_fixup_f32 v20, v20, v17, 1.0
	v_fma_f32 v17, -v22, v24, 1.0
	v_fmac_f32_e32 v24, v17, v24
	v_div_scale_f32 v17, vcc, 1.0, v16, 1.0
	v_mul_f32_e32 v21, v17, v24
	v_fma_f32 v23, -v22, v21, v17
	v_fmac_f32_e32 v21, v23, v24
	v_fma_f32 v17, -v22, v21, v17
	v_div_fmas_f32 v17, v17, v24, v21
	v_div_fixup_f32 v21, v17, v16, 1.0
	v_mul_f32_e32 v12, v12, v21
	v_mul_f32_e32 v4, v4, v21
	v_mul_f32_e32 v0, v0, v21
	v_mul_f32_e32 v8, v8, v21
	v_mul_f32_e32 v13, v13, v20
	v_mul_f32_e32 v5, v5, v20
	v_mul_f32_e32 v1, v1, v20
	v_mul_f32_e32 v9, v9, v20
	v_mul_f32_e32 v14, v14, v18
	v_mul_f32_e32 v6, v6, v18
	v_mul_f32_e32 v2, v2, v18
	v_mul_f32_e32 v10, v10, v18
	v_mul_f32_e32 v15, v15, v19
	v_mul_f32_e32 v7, v7, v19
	v_mul_f32_e32 v3, v3, v19
	v_mul_f32_e32 v11, v11, v19
	v_lshl_add_u32 v25, v116, 1, s47
	v_cvt_pk_bf16_f32 v12, v12, v4
	v_cvt_pk_bf16_f32 v0, v0, v8
	v_cvt_pk_bf16_f32 v13, v13, v5
	v_cvt_pk_bf16_f32 v1, v1, v9
	v_cvt_pk_bf16_f32 v14, v14, v6
	v_cvt_pk_bf16_f32 v2, v2, v10
	v_cvt_pk_bf16_f32 v15, v15, v7
	v_cvt_pk_bf16_f32 v3, v3, v11
	ds_write_b16 v25, v12 offset:1024
	ds_write_b16_d16_hi v25, v12 offset:1056
	ds_write_b16 v25, v0 offset:1088
	ds_write_b16_d16_hi v25, v0 offset:1120
	ds_write_b16 v25, v13 offset:1152
	ds_write_b16_d16_hi v25, v13 offset:1184
	ds_write_b16 v25, v1 offset:1216
	ds_write_b16_d16_hi v25, v1 offset:1248
	ds_write_b16 v25, v14 offset:1280
	ds_write_b16_d16_hi v25, v14 offset:1312
	ds_write_b16 v25, v2 offset:1344
	ds_write_b16_d16_hi v25, v2 offset:1376
	ds_write_b16 v25, v15 offset:1408
	ds_write_b16_d16_hi v25, v15 offset:1440
	ds_write_b16 v25, v3 offset:1472
	ds_write_b16_d16_hi v25, v3 offset:1504
	s_mov_b32 exec_lo, -1
	s_mov_b32 exec_hi, 0
	v_lshl_add_u32 v26, v117, 4, s47
	v_lshlrev_b32_e32 v27, 4, v117
	s_add_u32 s18, s16, s14
	s_addc_u32 s19, s17, s15
	ds_read_b128 v[28:31], v26 offset:1024
	s_waitcnt lgkmcnt(0)
	global_store_dwordx4 v27, v[28:31], s[18:19]
	s_branch .LBB0_1251
